# v12 + EpiRes (w_out and mlp2) non-split epilogues: f32 accumulators transposed across lanes through per-wave LDS slices so residual loads and output stores touch full 128-B row segments, residual load
# speedup vs baseline: 1.0358x; 1.0107x over previous
;     DI void operator()(const f32x4 (&acc)[2][2][4][2], const Unit& u, int wr, int wc, int fr, int fq) const {
;         const int b = u.pm / 17, tl = u.pm % 17;
;         const float* rbase = from_input ? xin_tile(P, b, tl) : xst_tile(P, b, tl);
;         float* dbase = xst_tile(P, b, tl);
;         const float* garow = ga + (size_t)(tl == 0 ? 8 : b) * 6144;
;         const int rin = wr * 64 + fr, col0 = u.pn * BM + wc * 32 + 8 * fq;
; #pragma unroll
;         for (int bj = 0; bj < 2; ++bj) { const int col = col0 + bj * HALF; const f32x4 g0 = *(const f32x4*)(garow + col), g1 = *(const f32x4*)(garow + col + 4);
; #pragma unroll
;             for (int ai = 0; ai < 2; ++ai)
; #pragma unroll
;                 for (int m = 0; m < 4; ++m) { const size_t off = (size_t)(rin + ai * HALF + m * 16) * D + col;
;                     if (u.split) { float* sp = (float*)(P.ws + WS_SLAB) + ((size_t)u.sl * (NB * CTX) + (size_t)b * CTX) * D + off;
;                         *(f32x4*)sp = g0 * acc[ai][bj][m][0]; *(f32x4*)(sp + 4) = g1 * acc[ai][bj][m][1]; }
;                     else { const f32x4 x0 = *(const f32x4*)(rbase + off), x1 = *(const f32x4*)(rbase + off + 4);
;                         *(f32x4*)(dbase + off) = x0 + g0 * acc[ai][bj][m][0]; *(f32x4*)(dbase + off + 4) = x1 + g1 * acc[ai][bj][m][1]; } } }
.LBB0_773:
	v_lshl_add_u64 v[0:1], v[76:77], 2, s[0:1]
	s_andn2_b64 vcc, exec, s[8:9]
	s_mov_b64 s[0:1], -1
	global_store_dwordx4 v[0:1], v[8:11], off offset:528
	s_cbranch_vccnz .LBB0_686
.Lepi_wo_after:
	v_readlane_b32 s0, v254, 58
	v_readlane_b32 s1, v254, 59
	s_and_b64 vcc, exec, s[0:1]
	s_cbranch_vccnz .LBB0_685
	s_barrier
	s_branch .LBB0_685
.Lepi_wo_fast:
	v_mbcnt_lo_u32_b32 v204, -1, 0
	v_mbcnt_hi_u32_b32 v204, -1, v204
	v_readfirstlane_b32 s78, v182
	v_readfirstlane_b32 s79, v154
	v_readfirstlane_b32 s80, v178
	v_readfirstlane_b32 s81, v179
	v_readlane_b32 s82, v253, 14
	v_and_b32_e32 v211, 7, v204
	v_lshrrev_b32_e32 v205, 4, v204
	v_lshlrev_b32_e32 v205, 1, v205
	v_xor_b32_e32 v205, v205, v211
	v_lshlrev_b32_e32 v205, 4, v205
	v_lshl_or_b32 v205, v211, 7, v205
	v_bfe_u32 v206, v204, 3, 1
	v_lshl_or_b32 v205, v206, 13, v205
	v_lshrrev_b32_e32 v207, 3, v204
	v_xor_b32_e32 v209, v211, v207
	v_lshlrev_b32_e32 v209, 4, v209
	v_lshlrev_b32_e32 v210, 4, v211
	v_lshl_or_b32 v208, v207, 12, v210
	v_lshl_or_b32 v207, v207, 7, v209
	s_add_i32 s82, s82, 0xc000
	v_add_u32_e32 v205, s82, v205
	v_xor_b32_e32 v206, 16, v205
	v_add_u32_e32 v207, s82, v207
	v_add_u32_e32 v209, 0x8000, v208
	s_add_i32 s78, s78, s79
	s_lshl_b32 s78, s78, 2
	s_add_u32 s74, s18, s78
	s_addc_u32 s75, s19, 0
	s_add_u32 s76, s16, s78
	s_addc_u32 s77, s17, 0
	global_load_dwordx4 v[212:215], v210, s[80:81]
	global_load_dwordx4 v[216:219], v210, s[80:81] offset:512
	global_load_dwordx4 v[236:239], v208, s[74:75]
	global_load_dwordx4 v[240:243], v209, s[74:75]
	global_load_dwordx4 v[244:247], v208, s[74:75] offset:512
	global_load_dwordx4 v[192:195], v209, s[74:75] offset:512
	s_add_u32 s74, s74, 0x10000
	s_addc_u32 s75, s75, 0
	global_load_dwordx4 v[196:199], v208, s[74:75]
	global_load_dwordx4 v[186:189], v209, s[74:75]
	ds_write_b128 v205, v[126:129]
	ds_write_b128 v206, v[122:125]
	ds_read_b128 v[220:223], v207
	ds_read_b128 v[224:227], v207 offset:8192
	ds_write_b128 v205, v[60:63]
	ds_write_b128 v206, v[56:59]
	ds_read_b128 v[228:231], v207
	ds_read_b128 v[232:235], v207 offset:8192
	s_waitcnt vmcnt(5) lgkmcnt(5)
	v_pk_fma_f32 v[220:221], v[220:221], v[212:213], v[236:237]
	v_pk_fma_f32 v[222:223], v[222:223], v[214:215], v[238:239]
	global_store_dwordx4 v208, v[220:223], s[76:77]
	global_load_dwordx4 v[236:239], v208, s[74:75] offset:512
	s_waitcnt vmcnt(6) lgkmcnt(4)
	v_pk_fma_f32 v[224:225], v[224:225], v[212:213], v[240:241]
	v_pk_fma_f32 v[226:227], v[226:227], v[214:215], v[242:243]
	global_store_dwordx4 v209, v[224:227], s[76:77]
	global_load_dwordx4 v[240:243], v209, s[74:75] offset:512
	ds_write_b128 v205, v[118:121]
	ds_write_b128 v206, v[114:117]
	ds_read_b128 v[220:223], v207
	ds_read_b128 v[224:227], v207 offset:8192
	s_waitcnt vmcnt(7) lgkmcnt(5)
	v_pk_fma_f32 v[228:229], v[228:229], v[216:217], v[244:245]
	v_pk_fma_f32 v[230:231], v[230:231], v[218:219], v[246:247]
	global_store_dwordx4 v208, v[228:231], s[76:77] offset:512
	s_add_u32 s74, s74, 0x10000
	s_addc_u32 s75, s75, 0
	global_load_dwordx4 v[244:247], v208, s[74:75]
	s_waitcnt vmcnt(8) lgkmcnt(4)
	v_pk_fma_f32 v[232:233], v[232:233], v[216:217], v[192:193]
	v_pk_fma_f32 v[234:235], v[234:235], v[218:219], v[194:195]
	global_store_dwordx4 v209, v[232:235], s[76:77] offset:512
	global_load_dwordx4 v[192:195], v209, s[74:75]
	ds_write_b128 v205, v[52:55]
	ds_write_b128 v206, v[48:51]
	ds_read_b128 v[228:231], v207
	ds_read_b128 v[232:235], v207 offset:8192
	s_waitcnt vmcnt(9) lgkmcnt(5)
	v_pk_fma_f32 v[220:221], v[220:221], v[212:213], v[196:197]
	v_pk_fma_f32 v[222:223], v[222:223], v[214:215], v[198:199]
	s_add_u32 s76, s76, 0x10000
	s_addc_u32 s77, s77, 0
	global_store_dwordx4 v208, v[220:223], s[76:77]
	global_load_dwordx4 v[196:199], v208, s[74:75] offset:512
	s_waitcnt vmcnt(10) lgkmcnt(4)
	v_pk_fma_f32 v[224:225], v[224:225], v[212:213], v[186:187]
	v_pk_fma_f32 v[226:227], v[226:227], v[214:215], v[188:189]
	global_store_dwordx4 v209, v[224:227], s[76:77]
	global_load_dwordx4 v[186:189], v209, s[74:75] offset:512
	ds_write_b128 v205, v[108:111]
	ds_write_b128 v206, v[104:107]
	ds_read_b128 v[220:223], v207
	ds_read_b128 v[224:227], v207 offset:8192
	s_waitcnt vmcnt(10) lgkmcnt(5)
	v_pk_fma_f32 v[228:229], v[228:229], v[216:217], v[236:237]
	v_pk_fma_f32 v[230:231], v[230:231], v[218:219], v[238:239]
	global_store_dwordx4 v208, v[228:231], s[76:77] offset:512
	s_add_u32 s74, s74, 0x10000
	s_addc_u32 s75, s75, 0
	global_load_dwordx4 v[236:239], v208, s[74:75]
	s_waitcnt vmcnt(10) lgkmcnt(4)
	v_pk_fma_f32 v[232:233], v[232:233], v[216:217], v[240:241]
	v_pk_fma_f32 v[234:235], v[234:235], v[218:219], v[242:243]
	global_store_dwordx4 v209, v[232:235], s[76:77] offset:512
	global_load_dwordx4 v[240:243], v209, s[74:75]
	ds_write_b128 v205, v[44:47]
	ds_write_b128 v206, v[40:43]
	ds_read_b128 v[228:231], v207
	ds_read_b128 v[232:235], v207 offset:8192
	s_waitcnt vmcnt(10) lgkmcnt(5)
	v_pk_fma_f32 v[220:221], v[220:221], v[212:213], v[244:245]
	v_pk_fma_f32 v[222:223], v[222:223], v[214:215], v[246:247]
	s_add_u32 s76, s76, 0x10000
	s_addc_u32 s77, s77, 0
	global_store_dwordx4 v208, v[220:223], s[76:77]
	global_load_dwordx4 v[244:247], v208, s[74:75] offset:512
	s_waitcnt vmcnt(10) lgkmcnt(4)
	v_pk_fma_f32 v[224:225], v[224:225], v[212:213], v[192:193]
	v_pk_fma_f32 v[226:227], v[226:227], v[214:215], v[194:195]
	global_store_dwordx4 v209, v[224:227], s[76:77]
	global_load_dwordx4 v[192:195], v209, s[74:75] offset:512
	ds_write_b128 v205, v[100:103]
	ds_write_b128 v206, v[96:99]
	ds_read_b128 v[220:223], v207
	ds_read_b128 v[224:227], v207 offset:8192
	s_waitcnt vmcnt(10) lgkmcnt(5)
;     DI void operator()(const f32x4 (&acc)[2][2][4][2], const Unit& u, int wr, int wc, int fr, int fq) const {
;     ...
;         for (int bj = 0; bj < 2; ++bj) { const int col = col0 + bj * HALF; const f32x4 g0 = *(const f32x4*)(garow + col), g1 = *(const f32x4*)(garow + col + 4);
; #pragma unroll
;             for (int ai = 0; ai < 2; ++ai)
; #pragma unroll
;                 for (int m = 0; m < 4; ++m) { const size_t off = (size_t)(rin + ai * HALF + m * 16) * D + col;
;                     if (u.split) { float* sp = (float*)(P.ws + WS_SLAB) + ((size_t)u.sl * (NB * CTX) + (size_t)b * CTX) * D + off;
;                         *(f32x4*)sp = g0 * acc[ai][bj][m][0]; *(f32x4*)(sp + 4) = g1 * acc[ai][bj][m][1]; }
;                     else { const f32x4 x0 = *(const f32x4*)(rbase + off), x1 = *(const f32x4*)(rbase + off + 4);
;                         *(f32x4*)(dbase + off) = x0 + g0 * acc[ai][bj][m][0]; *(f32x4*)(dbase + off + 4) = x1 + g1 * acc[ai][bj][m][1]; } } }
	v_pk_fma_f32 v[228:229], v[228:229], v[216:217], v[196:197]
	v_pk_fma_f32 v[230:231], v[230:231], v[218:219], v[198:199]
	global_store_dwordx4 v208, v[228:231], s[76:77] offset:512
	s_add_u32 s74, s74, 0x50000
	s_addc_u32 s75, s75, 0
	global_load_dwordx4 v[196:199], v208, s[74:75]
	s_waitcnt vmcnt(10) lgkmcnt(4)
	v_pk_fma_f32 v[232:233], v[232:233], v[216:217], v[186:187]
	v_pk_fma_f32 v[234:235], v[234:235], v[218:219], v[188:189]
	global_store_dwordx4 v209, v[232:235], s[76:77] offset:512
	global_load_dwordx4 v[186:189], v209, s[74:75]
	ds_write_b128 v205, v[36:39]
	ds_write_b128 v206, v[32:35]
	ds_read_b128 v[228:231], v207
	ds_read_b128 v[232:235], v207 offset:8192
	s_waitcnt vmcnt(10) lgkmcnt(5)
	v_pk_fma_f32 v[220:221], v[220:221], v[212:213], v[236:237]
	v_pk_fma_f32 v[222:223], v[222:223], v[214:215], v[238:239]
	s_add_u32 s76, s76, 0x10000
	s_addc_u32 s77, s77, 0
	global_store_dwordx4 v208, v[220:223], s[76:77]
	global_load_dwordx4 v[236:239], v208, s[74:75] offset:512
	s_waitcnt vmcnt(10) lgkmcnt(4)
	v_pk_fma_f32 v[224:225], v[224:225], v[212:213], v[240:241]
	v_pk_fma_f32 v[226:227], v[226:227], v[214:215], v[242:243]
	global_store_dwordx4 v209, v[224:227], s[76:77]
	global_load_dwordx4 v[240:243], v209, s[74:75] offset:512
	ds_write_b128 v205, v[92:95]
	ds_write_b128 v206, v[88:91]
	ds_read_b128 v[220:223], v207
	ds_read_b128 v[224:227], v207 offset:8192
	s_waitcnt vmcnt(10) lgkmcnt(5)
	v_pk_fma_f32 v[228:229], v[228:229], v[216:217], v[244:245]
	v_pk_fma_f32 v[230:231], v[230:231], v[218:219], v[246:247]
	global_store_dwordx4 v208, v[228:231], s[76:77] offset:512
	s_add_u32 s74, s74, 0x10000
	s_addc_u32 s75, s75, 0
	global_load_dwordx4 v[244:247], v208, s[74:75]
	s_waitcnt vmcnt(10) lgkmcnt(4)
	v_pk_fma_f32 v[232:233], v[232:233], v[216:217], v[192:193]
	v_pk_fma_f32 v[234:235], v[234:235], v[218:219], v[194:195]
	global_store_dwordx4 v209, v[232:235], s[76:77] offset:512
	global_load_dwordx4 v[192:195], v209, s[74:75]
	ds_write_b128 v205, v[28:31]
	ds_write_b128 v206, v[24:27]
	ds_read_b128 v[228:231], v207
	ds_read_b128 v[232:235], v207 offset:8192
	s_waitcnt vmcnt(10) lgkmcnt(5)
	v_pk_fma_f32 v[220:221], v[220:221], v[212:213], v[196:197]
	v_pk_fma_f32 v[222:223], v[222:223], v[214:215], v[198:199]
	s_add_u32 s76, s76, 0x50000
	s_addc_u32 s77, s77, 0
	global_store_dwordx4 v208, v[220:223], s[76:77]
	global_load_dwordx4 v[196:199], v208, s[74:75] offset:512
	s_waitcnt vmcnt(10) lgkmcnt(4)
	v_pk_fma_f32 v[224:225], v[224:225], v[212:213], v[186:187]
	v_pk_fma_f32 v[226:227], v[226:227], v[214:215], v[188:189]
	global_store_dwordx4 v209, v[224:227], s[76:77]
	global_load_dwordx4 v[186:189], v209, s[74:75] offset:512
	ds_write_b128 v205, v[84:87]
	ds_write_b128 v206, v[80:83]
	ds_read_b128 v[220:223], v207
	ds_read_b128 v[224:227], v207 offset:8192
	s_waitcnt vmcnt(10) lgkmcnt(5)
	v_pk_fma_f32 v[228:229], v[228:229], v[216:217], v[236:237]
	v_pk_fma_f32 v[230:231], v[230:231], v[218:219], v[238:239]
	global_store_dwordx4 v208, v[228:231], s[76:77] offset:512
	s_add_u32 s74, s74, 0x10000
	s_addc_u32 s75, s75, 0
	global_load_dwordx4 v[236:239], v208, s[74:75]
	s_waitcnt vmcnt(10) lgkmcnt(4)
	v_pk_fma_f32 v[232:233], v[232:233], v[216:217], v[240:241]
	v_pk_fma_f32 v[234:235], v[234:235], v[218:219], v[242:243]
	global_store_dwordx4 v209, v[232:235], s[76:77] offset:512
	global_load_dwordx4 v[240:243], v209, s[74:75]
	ds_write_b128 v205, v[20:23]
	ds_write_b128 v206, v[16:19]
	ds_read_b128 v[228:231], v207
	ds_read_b128 v[232:235], v207 offset:8192
	s_waitcnt vmcnt(10) lgkmcnt(5)
; template <class Epi>
; DI void gemm_phase(LAS unsigned char* lds, const Gemm g, const Order& S, const Epi& E, const int wv) {
;     ...
;         if (!has_next) break;
;     DI void operator()(const f32x4 (&acc)[2][2][4][2], const Unit& u, int wr, int wc, int fr, int fq) const {
;     ...
;         for (int bj = 0; bj < 2; ++bj) { const int col = col0 + bj * HALF; const f32x4 g0 = *(const f32x4*)(garow + col), g1 = *(const f32x4*)(garow + col + 4);
; #pragma unroll
;             for (int ai = 0; ai < 2; ++ai)
; #pragma unroll
;                 for (int m = 0; m < 4; ++m) { const size_t off = (size_t)(rin + ai * HALF + m * 16) * D + col;
;                     if (u.split) { float* sp = (float*)(P.ws + WS_SLAB) + ((size_t)u.sl * (NB * CTX) + (size_t)b * CTX) * D + off;
;                         *(f32x4*)sp = g0 * acc[ai][bj][m][0]; *(f32x4*)(sp + 4) = g1 * acc[ai][bj][m][1]; }
;                     else { const f32x4 x0 = *(const f32x4*)(rbase + off), x1 = *(const f32x4*)(rbase + off + 4);
;                         *(f32x4*)(dbase + off) = x0 + g0 * acc[ai][bj][m][0]; *(f32x4*)(dbase + off + 4) = x1 + g1 * acc[ai][bj][m][1]; } } }
	v_pk_fma_f32 v[220:221], v[220:221], v[212:213], v[244:245]
	v_pk_fma_f32 v[222:223], v[222:223], v[214:215], v[246:247]
	s_add_u32 s76, s76, 0x10000
	s_addc_u32 s77, s77, 0
	global_store_dwordx4 v208, v[220:223], s[76:77]
	global_load_dwordx4 v[244:247], v208, s[74:75] offset:512
	s_waitcnt vmcnt(10) lgkmcnt(4)
	v_pk_fma_f32 v[224:225], v[224:225], v[212:213], v[192:193]
	v_pk_fma_f32 v[226:227], v[226:227], v[214:215], v[194:195]
	global_store_dwordx4 v209, v[224:227], s[76:77]
	global_load_dwordx4 v[192:195], v209, s[74:75] offset:512
	ds_write_b128 v205, v[76:79]
	ds_write_b128 v206, v[72:75]
	ds_read_b128 v[220:223], v207
	ds_read_b128 v[224:227], v207 offset:8192
	s_waitcnt vmcnt(10) lgkmcnt(5)
	v_pk_fma_f32 v[228:229], v[228:229], v[216:217], v[196:197]
	v_pk_fma_f32 v[230:231], v[230:231], v[218:219], v[198:199]
	global_store_dwordx4 v208, v[228:231], s[76:77] offset:512
	s_add_u32 s74, s74, 0x10000
	s_addc_u32 s75, s75, 0
	global_load_dwordx4 v[196:199], v208, s[74:75]
	s_waitcnt vmcnt(10) lgkmcnt(4)
	v_pk_fma_f32 v[232:233], v[232:233], v[216:217], v[186:187]
	v_pk_fma_f32 v[234:235], v[234:235], v[218:219], v[188:189]
	global_store_dwordx4 v209, v[232:235], s[76:77] offset:512
	global_load_dwordx4 v[186:189], v209, s[74:75]
	ds_write_b128 v205, v[12:15]
	ds_write_b128 v206, v[8:11]
	ds_read_b128 v[228:231], v207
	ds_read_b128 v[232:235], v207 offset:8192
	s_waitcnt vmcnt(10) lgkmcnt(5)
	v_pk_fma_f32 v[220:221], v[220:221], v[212:213], v[236:237]
	v_pk_fma_f32 v[222:223], v[222:223], v[214:215], v[238:239]
	s_add_u32 s76, s76, 0x10000
	s_addc_u32 s77, s77, 0
	global_store_dwordx4 v208, v[220:223], s[76:77]
	global_load_dwordx4 v[236:239], v208, s[74:75] offset:512
	s_waitcnt vmcnt(10) lgkmcnt(4)
	v_pk_fma_f32 v[224:225], v[224:225], v[212:213], v[240:241]
	v_pk_fma_f32 v[226:227], v[226:227], v[214:215], v[242:243]
	global_store_dwordx4 v209, v[224:227], s[76:77]
	global_load_dwordx4 v[240:243], v209, s[74:75] offset:512
	ds_write_b128 v205, v[68:71]
	ds_write_b128 v206, v[64:67]
	ds_read_b128 v[220:223], v207
	ds_read_b128 v[224:227], v207 offset:8192
	s_waitcnt vmcnt(10) lgkmcnt(5)
	v_pk_fma_f32 v[228:229], v[228:229], v[216:217], v[244:245]
	v_pk_fma_f32 v[230:231], v[230:231], v[218:219], v[246:247]
	global_store_dwordx4 v208, v[228:231], s[76:77] offset:512
	s_waitcnt vmcnt(9) lgkmcnt(4)
	v_pk_fma_f32 v[232:233], v[232:233], v[216:217], v[192:193]
	v_pk_fma_f32 v[234:235], v[234:235], v[218:219], v[194:195]
	global_store_dwordx4 v209, v[232:235], s[76:77] offset:512
	ds_write_b128 v205, v[4:7]
	ds_write_b128 v206, v[0:3]
	ds_read_b128 v[228:231], v207
	ds_read_b128 v[232:235], v207 offset:8192
	s_waitcnt vmcnt(8) lgkmcnt(5)
	v_pk_fma_f32 v[220:221], v[220:221], v[212:213], v[196:197]
	v_pk_fma_f32 v[222:223], v[222:223], v[214:215], v[198:199]
	s_add_u32 s76, s76, 0x10000
	s_addc_u32 s77, s77, 0
	global_store_dwordx4 v208, v[220:223], s[76:77]
	s_waitcnt vmcnt(7) lgkmcnt(4)
	v_pk_fma_f32 v[224:225], v[224:225], v[212:213], v[186:187]
	v_pk_fma_f32 v[226:227], v[226:227], v[214:215], v[188:189]
	global_store_dwordx4 v209, v[224:227], s[76:77]
	s_waitcnt vmcnt(6) lgkmcnt(1)
	v_pk_fma_f32 v[228:229], v[228:229], v[216:217], v[236:237]
	v_pk_fma_f32 v[230:231], v[230:231], v[218:219], v[238:239]
	global_store_dwordx4 v208, v[228:231], s[76:77] offset:512
	s_waitcnt vmcnt(5) lgkmcnt(0)
	v_pk_fma_f32 v[232:233], v[232:233], v[216:217], v[240:241]
	v_pk_fma_f32 v[234:235], v[234:235], v[218:219], v[242:243]
	global_store_dwordx4 v209, v[232:235], s[76:77] offset:512
	s_andn2_b64 vcc, exec, s[8:9]
	s_mov_b64 s[0:1], -1
	s_cbranch_vccnz .LBB0_686
	s_branch .Lepi_wo_after

;     DI void operator()(const f32x4 (&acc)[2][2][4][2], const Unit& u, int wr, int wc, int fr, int fq) const {
;         const int b = u.pm / 17, tl = u.pm % 17;
;         const float* rbase = from_input ? xin_tile(P, b, tl) : xst_tile(P, b, tl);
;         float* dbase = xst_tile(P, b, tl);
;         const float* garow = ga + (size_t)(tl == 0 ? 8 : b) * 6144;
;         const int rin = wr * 64 + fr, col0 = u.pn * BM + wc * 32 + 8 * fq;
; #pragma unroll
;         for (int bj = 0; bj < 2; ++bj) { const int col = col0 + bj * HALF; const f32x4 g0 = *(const f32x4*)(garow + col), g1 = *(const f32x4*)(garow + col + 4);
; #pragma unroll
;             for (int ai = 0; ai < 2; ++ai)
; #pragma unroll
;                 for (int m = 0; m < 4; ++m) { const size_t off = (size_t)(rin + ai * HALF + m * 16) * D + col;
;                     if (u.split) { float* sp = (float*)(P.ws + WS_SLAB) + ((size_t)u.sl * (NB * CTX) + (size_t)b * CTX) * D + off;
;                         *(f32x4*)sp = g0 * acc[ai][bj][m][0]; *(f32x4*)(sp + 4) = g1 * acc[ai][bj][m][1]; }
;                     else { const f32x4 x0 = *(const f32x4*)(rbase + off), x1 = *(const f32x4*)(rbase + off + 4);
.LBB0_997:
	v_mov_b32_e32 v149, s17
	v_cndmask_b32_e64 v153, v175, v149, s[0:1]
	v_mov_b32_e32 v149, s16
	v_cndmask_b32_e64 v152, v174, v149, s[0:1]
	v_lshlrev_b64 v[152:153], 20, v[152:153]
	v_lshl_add_u64 v[186:187], s[22:23], 0, v[152:153]
	v_lshlrev_b64 v[152:153], 20, v[178:179]
	v_lshl_add_u64 v[174:175], s[20:21], 0, v[152:153]
	v_lshlrev_b64 v[152:153], 2, v[176:177]
	s_andn2_b64 vcc, exec, s[26:27]
	v_mov_b64_e32 v[188:189], s[24:25]
	v_lshl_add_u64 v[182:183], v[186:187], 0, v[152:153]
	v_lshl_add_u64 v[178:179], v[174:175], 0, v[152:153]
	s_cbranch_vccnz .LBB0_999
	s_branch .Lepi_m2_fast
	global_load_dwordx4 v[138:141], v[182:183], off
	global_load_dwordx4 v[192:195], v[182:183], off offset:16
	v_mov_b64_e32 v[188:189], v[174:175]
	s_waitcnt vmcnt(0)
	v_pk_fma_f32 v[128:129], v[128:129], v[136:137], v[140:141]
	v_pk_fma_f32 v[126:127], v[126:127], v[134:135], v[138:139]
	v_pk_fma_f32 v[140:141], v[124:125], v[132:133], v[194:195]
	v_pk_fma_f32 v[138:139], v[122:123], v[130:131], v[192:193]
	global_store_dwordx4 v[178:179], v[126:129], off

;     DI void operator()(const f32x4 (&acc)[2][2][4][2], const Unit& u, int wr, int wc, int fr, int fq) const {
;         const int b = u.pm / 17, tl = u.pm % 17;
;         const float* rbase = from_input ? xin_tile(P, b, tl) : xst_tile(P, b, tl);
;         float* dbase = xst_tile(P, b, tl);
;         const float* garow = ga + (size_t)(tl == 0 ? 8 : b) * 6144;
;         const int rin = wr * 64 + fr, col0 = u.pn * BM + wc * 32 + 8 * fq;
; #pragma unroll
;         for (int bj = 0; bj < 2; ++bj) { const int col = col0 + bj * HALF; const f32x4 g0 = *(const f32x4*)(garow + col), g1 = *(const f32x4*)(garow + col + 4);
; #pragma unroll
;             for (int ai = 0; ai < 2; ++ai)
; #pragma unroll
;                 for (int m = 0; m < 4; ++m) { const size_t off = (size_t)(rin + ai * HALF + m * 16) * D + col;
;                     if (u.split) { float* sp = (float*)(P.ws + WS_SLAB) + ((size_t)u.sl * (NB * CTX) + (size_t)b * CTX) * D + off;
;                         *(f32x4*)sp = g0 * acc[ai][bj][m][0]; *(f32x4*)(sp + 4) = g1 * acc[ai][bj][m][1]; }
;                     else { const f32x4 x0 = *(const f32x4*)(rbase + off), x1 = *(const f32x4*)(rbase + off + 4);
;                         *(f32x4*)(dbase + off) = x0 + g0 * acc[ai][bj][m][0]; *(f32x4*)(dbase + off + 4) = x1 + g1 * acc[ai][bj][m][1]; } } }
.LBB0_1058:
	v_lshl_add_u64 v[0:1], v[76:77], 2, v[12:13]
	s_andn2_b64 vcc, exec, s[8:9]
	s_mov_b64 s[0:1], -1
	global_store_dwordx4 v[0:1], v[8:11], off offset:528
	s_cbranch_vccnz .LBB0_976
.Lepi_m2_after:
	v_readlane_b32 s0, v254, 58
	v_readlane_b32 s1, v254, 59
	s_and_b64 vcc, exec, s[0:1]
	s_cbranch_vccnz .LBB0_975
	s_barrier
	s_branch .LBB0_975
.Lepi_m2_fast:
	v_mbcnt_lo_u32_b32 v206, -1, 0
	v_mbcnt_hi_u32_b32 v206, -1, v206
	v_readfirstlane_b32 s78, v184
	v_readfirstlane_b32 s79, v154
	v_readfirstlane_b32 s80, v180
	v_readfirstlane_b32 s81, v181
	v_readlane_b32 s82, v253, 14
	v_readfirstlane_b32 s74, v186
	v_readfirstlane_b32 s75, v187
	v_readfirstlane_b32 s76, v174
	v_readfirstlane_b32 s77, v175
	v_and_b32_e32 v213, 7, v206
	v_lshrrev_b32_e32 v207, 4, v206
	v_lshlrev_b32_e32 v207, 1, v207
	v_xor_b32_e32 v207, v207, v213
	v_lshlrev_b32_e32 v207, 4, v207
	v_lshl_or_b32 v207, v213, 7, v207
	v_bfe_u32 v208, v206, 3, 1
	v_lshl_or_b32 v207, v208, 13, v207
	v_lshrrev_b32_e32 v209, 3, v206
	v_xor_b32_e32 v211, v213, v209
	v_lshlrev_b32_e32 v211, 4, v211
	v_lshlrev_b32_e32 v212, 4, v213
	v_lshl_or_b32 v210, v209, 12, v212
	v_lshl_or_b32 v209, v209, 7, v211
	s_add_i32 s82, s82, 0xc000
	v_add_u32_e32 v207, s82, v207
	v_xor_b32_e32 v208, 16, v207
	v_add_u32_e32 v209, s82, v209
	v_add_u32_e32 v211, 0x8000, v210
	s_add_i32 s78, s78, s79
	s_lshl_b32 s78, s78, 2
	s_add_u32 s74, s74, s78
	s_addc_u32 s75, s75, 0
	s_add_u32 s76, s76, s78
	s_addc_u32 s77, s77, 0
	global_load_dwordx4 v[214:217], v212, s[80:81]
	global_load_dwordx4 v[218:221], v212, s[80:81] offset:512
	global_load_dwordx4 v[238:241], v210, s[74:75]
	global_load_dwordx4 v[242:245], v211, s[74:75]
	global_load_dwordx4 v[246:249], v210, s[74:75] offset:512
	global_load_dwordx4 v[192:195], v211, s[74:75] offset:512
	s_add_u32 s74, s74, 0x10000
	s_addc_u32 s75, s75, 0
	global_load_dwordx4 v[196:199], v210, s[74:75]
	global_load_dwordx4 v[186:189], v211, s[74:75]
	ds_write_b128 v207, v[126:129]
	ds_write_b128 v208, v[122:125]
	ds_read_b128 v[222:225], v209
	ds_read_b128 v[226:229], v209 offset:8192
	ds_write_b128 v207, v[60:63]
	ds_write_b128 v208, v[56:59]
	ds_read_b128 v[230:233], v209
	ds_read_b128 v[234:237], v209 offset:8192
	s_waitcnt vmcnt(5) lgkmcnt(5)
	v_pk_fma_f32 v[222:223], v[222:223], v[214:215], v[238:239]
	v_pk_fma_f32 v[224:225], v[224:225], v[216:217], v[240:241]
	global_store_dwordx4 v210, v[222:225], s[76:77]
	global_load_dwordx4 v[238:241], v210, s[74:75] offset:512
	s_waitcnt vmcnt(6) lgkmcnt(4)
	v_pk_fma_f32 v[226:227], v[226:227], v[214:215], v[242:243]
	v_pk_fma_f32 v[228:229], v[228:229], v[216:217], v[244:245]
	global_store_dwordx4 v211, v[226:229], s[76:77]
	global_load_dwordx4 v[242:245], v211, s[74:75] offset:512
	ds_write_b128 v207, v[118:121]
	ds_write_b128 v208, v[114:117]
	ds_read_b128 v[222:225], v209
	ds_read_b128 v[226:229], v209 offset:8192
	s_waitcnt vmcnt(7) lgkmcnt(5)
	v_pk_fma_f32 v[230:231], v[230:231], v[218:219], v[246:247]
	v_pk_fma_f32 v[232:233], v[232:233], v[220:221], v[248:249]
	global_store_dwordx4 v210, v[230:233], s[76:77] offset:512
	s_add_u32 s74, s74, 0x10000
	s_addc_u32 s75, s75, 0
	global_load_dwordx4 v[246:249], v210, s[74:75]
	s_waitcnt vmcnt(8) lgkmcnt(4)
	v_pk_fma_f32 v[234:235], v[234:235], v[218:219], v[192:193]
	v_pk_fma_f32 v[236:237], v[236:237], v[220:221], v[194:195]
	global_store_dwordx4 v211, v[234:237], s[76:77] offset:512
	global_load_dwordx4 v[192:195], v211, s[74:75]
	ds_write_b128 v207, v[52:55]
	ds_write_b128 v208, v[48:51]
	ds_read_b128 v[230:233], v209
	ds_read_b128 v[234:237], v209 offset:8192
	s_waitcnt vmcnt(9) lgkmcnt(5)
	v_pk_fma_f32 v[222:223], v[222:223], v[214:215], v[196:197]
	v_pk_fma_f32 v[224:225], v[224:225], v[216:217], v[198:199]
	s_add_u32 s76, s76, 0x10000
	s_addc_u32 s77, s77, 0
	global_store_dwordx4 v210, v[222:225], s[76:77]
	global_load_dwordx4 v[196:199], v210, s[74:75] offset:512
	s_waitcnt vmcnt(10) lgkmcnt(4)
	v_pk_fma_f32 v[226:227], v[226:227], v[214:215], v[186:187]
	v_pk_fma_f32 v[228:229], v[228:229], v[216:217], v[188:189]
	global_store_dwordx4 v211, v[226:229], s[76:77]
	global_load_dwordx4 v[186:189], v211, s[74:75] offset:512
	ds_write_b128 v207, v[108:111]
	ds_write_b128 v208, v[104:107]
	ds_read_b128 v[222:225], v209
	ds_read_b128 v[226:229], v209 offset:8192
	s_waitcnt vmcnt(10) lgkmcnt(5)
	v_pk_fma_f32 v[230:231], v[230:231], v[218:219], v[238:239]
	v_pk_fma_f32 v[232:233], v[232:233], v[220:221], v[240:241]
	global_store_dwordx4 v210, v[230:233], s[76:77] offset:512
	s_add_u32 s74, s74, 0x10000
	s_addc_u32 s75, s75, 0
	global_load_dwordx4 v[238:241], v210, s[74:75]
	s_waitcnt vmcnt(10) lgkmcnt(4)
	v_pk_fma_f32 v[234:235], v[234:235], v[218:219], v[242:243]
	v_pk_fma_f32 v[236:237], v[236:237], v[220:221], v[244:245]
	global_store_dwordx4 v211, v[234:237], s[76:77] offset:512
	global_load_dwordx4 v[242:245], v211, s[74:75]
	ds_write_b128 v207, v[44:47]
	ds_write_b128 v208, v[40:43]
	ds_read_b128 v[230:233], v209
	ds_read_b128 v[234:237], v209 offset:8192
	s_waitcnt vmcnt(10) lgkmcnt(5)
	v_pk_fma_f32 v[222:223], v[222:223], v[214:215], v[246:247]
	v_pk_fma_f32 v[224:225], v[224:225], v[216:217], v[248:249]
	s_add_u32 s76, s76, 0x10000
	s_addc_u32 s77, s77, 0
	global_store_dwordx4 v210, v[222:225], s[76:77]
	global_load_dwordx4 v[246:249], v210, s[74:75] offset:512
	s_waitcnt vmcnt(10) lgkmcnt(4)
	v_pk_fma_f32 v[226:227], v[226:227], v[214:215], v[192:193]
	v_pk_fma_f32 v[228:229], v[228:229], v[216:217], v[194:195]
	global_store_dwordx4 v211, v[226:229], s[76:77]
	global_load_dwordx4 v[192:195], v211, s[74:75] offset:512
	ds_write_b128 v207, v[100:103]
	ds_write_b128 v208, v[96:99]
	ds_read_b128 v[222:225], v209
	ds_read_b128 v[226:229], v209 offset:8192
	s_waitcnt vmcnt(10) lgkmcnt(5)
;     DI void operator()(const f32x4 (&acc)[2][2][4][2], const Unit& u, int wr, int wc, int fr, int fq) const {
;     ...
;         for (int bj = 0; bj < 2; ++bj) { const int col = col0 + bj * HALF; const f32x4 g0 = *(const f32x4*)(garow + col), g1 = *(const f32x4*)(garow + col + 4);
; #pragma unroll
;             for (int ai = 0; ai < 2; ++ai)
; #pragma unroll
;                 for (int m = 0; m < 4; ++m) { const size_t off = (size_t)(rin + ai * HALF + m * 16) * D + col;
;                     if (u.split) { float* sp = (float*)(P.ws + WS_SLAB) + ((size_t)u.sl * (NB * CTX) + (size_t)b * CTX) * D + off;
;                         *(f32x4*)sp = g0 * acc[ai][bj][m][0]; *(f32x4*)(sp + 4) = g1 * acc[ai][bj][m][1]; }
;                     else { const f32x4 x0 = *(const f32x4*)(rbase + off), x1 = *(const f32x4*)(rbase + off + 4);
;                         *(f32x4*)(dbase + off) = x0 + g0 * acc[ai][bj][m][0]; *(f32x4*)(dbase + off + 4) = x1 + g1 * acc[ai][bj][m][1]; } } }
	v_pk_fma_f32 v[230:231], v[230:231], v[218:219], v[196:197]
	v_pk_fma_f32 v[232:233], v[232:233], v[220:221], v[198:199]
	global_store_dwordx4 v210, v[230:233], s[76:77] offset:512
	s_add_u32 s74, s74, 0x50000
	s_addc_u32 s75, s75, 0
	global_load_dwordx4 v[196:199], v210, s[74:75]
	s_waitcnt vmcnt(10) lgkmcnt(4)
	v_pk_fma_f32 v[234:235], v[234:235], v[218:219], v[186:187]
	v_pk_fma_f32 v[236:237], v[236:237], v[220:221], v[188:189]
	global_store_dwordx4 v211, v[234:237], s[76:77] offset:512
	global_load_dwordx4 v[186:189], v211, s[74:75]
	ds_write_b128 v207, v[36:39]
	ds_write_b128 v208, v[32:35]
	ds_read_b128 v[230:233], v209
	ds_read_b128 v[234:237], v209 offset:8192
	s_waitcnt vmcnt(10) lgkmcnt(5)
	v_pk_fma_f32 v[222:223], v[222:223], v[214:215], v[238:239]
	v_pk_fma_f32 v[224:225], v[224:225], v[216:217], v[240:241]
	s_add_u32 s76, s76, 0x10000
	s_addc_u32 s77, s77, 0
	global_store_dwordx4 v210, v[222:225], s[76:77]
	global_load_dwordx4 v[238:241], v210, s[74:75] offset:512
	s_waitcnt vmcnt(10) lgkmcnt(4)
	v_pk_fma_f32 v[226:227], v[226:227], v[214:215], v[242:243]
	v_pk_fma_f32 v[228:229], v[228:229], v[216:217], v[244:245]
	global_store_dwordx4 v211, v[226:229], s[76:77]
	global_load_dwordx4 v[242:245], v211, s[74:75] offset:512
	ds_write_b128 v207, v[92:95]
	ds_write_b128 v208, v[88:91]
	ds_read_b128 v[222:225], v209
	ds_read_b128 v[226:229], v209 offset:8192
	s_waitcnt vmcnt(10) lgkmcnt(5)
	v_pk_fma_f32 v[230:231], v[230:231], v[218:219], v[246:247]
	v_pk_fma_f32 v[232:233], v[232:233], v[220:221], v[248:249]
	global_store_dwordx4 v210, v[230:233], s[76:77] offset:512
	s_add_u32 s74, s74, 0x10000
	s_addc_u32 s75, s75, 0
	global_load_dwordx4 v[246:249], v210, s[74:75]
	s_waitcnt vmcnt(10) lgkmcnt(4)
	v_pk_fma_f32 v[234:235], v[234:235], v[218:219], v[192:193]
	v_pk_fma_f32 v[236:237], v[236:237], v[220:221], v[194:195]
	global_store_dwordx4 v211, v[234:237], s[76:77] offset:512
	global_load_dwordx4 v[192:195], v211, s[74:75]
	ds_write_b128 v207, v[28:31]
	ds_write_b128 v208, v[24:27]
	ds_read_b128 v[230:233], v209
	ds_read_b128 v[234:237], v209 offset:8192
	s_waitcnt vmcnt(10) lgkmcnt(5)
	v_pk_fma_f32 v[222:223], v[222:223], v[214:215], v[196:197]
	v_pk_fma_f32 v[224:225], v[224:225], v[216:217], v[198:199]
	s_add_u32 s76, s76, 0x50000
	s_addc_u32 s77, s77, 0
	global_store_dwordx4 v210, v[222:225], s[76:77]
	global_load_dwordx4 v[196:199], v210, s[74:75] offset:512
	s_waitcnt vmcnt(10) lgkmcnt(4)
	v_pk_fma_f32 v[226:227], v[226:227], v[214:215], v[186:187]
	v_pk_fma_f32 v[228:229], v[228:229], v[216:217], v[188:189]
	global_store_dwordx4 v211, v[226:229], s[76:77]
	global_load_dwordx4 v[186:189], v211, s[74:75] offset:512
	ds_write_b128 v207, v[84:87]
	ds_write_b128 v208, v[80:83]
	ds_read_b128 v[222:225], v209
	ds_read_b128 v[226:229], v209 offset:8192
	s_waitcnt vmcnt(10) lgkmcnt(5)
	v_pk_fma_f32 v[230:231], v[230:231], v[218:219], v[238:239]
	v_pk_fma_f32 v[232:233], v[232:233], v[220:221], v[240:241]
	global_store_dwordx4 v210, v[230:233], s[76:77] offset:512
	s_add_u32 s74, s74, 0x10000
	s_addc_u32 s75, s75, 0
	global_load_dwordx4 v[238:241], v210, s[74:75]
	s_waitcnt vmcnt(10) lgkmcnt(4)
	v_pk_fma_f32 v[234:235], v[234:235], v[218:219], v[242:243]
	v_pk_fma_f32 v[236:237], v[236:237], v[220:221], v[244:245]
	global_store_dwordx4 v211, v[234:237], s[76:77] offset:512
	global_load_dwordx4 v[242:245], v211, s[74:75]
	ds_write_b128 v207, v[20:23]
	ds_write_b128 v208, v[16:19]
	ds_read_b128 v[230:233], v209
	ds_read_b128 v[234:237], v209 offset:8192
	s_waitcnt vmcnt(10) lgkmcnt(5)
; template <class Epi>
; DI void gemm_phase(LAS unsigned char* lds, const Gemm g, const Order& S, const Epi& E, const int wv) {
;     ...
;         if (!has_next) break;
;     DI void operator()(const f32x4 (&acc)[2][2][4][2], const Unit& u, int wr, int wc, int fr, int fq) const {
;     ...
;         for (int bj = 0; bj < 2; ++bj) { const int col = col0 + bj * HALF; const f32x4 g0 = *(const f32x4*)(garow + col), g1 = *(const f32x4*)(garow + col + 4);
; #pragma unroll
;             for (int ai = 0; ai < 2; ++ai)
; #pragma unroll
;                 for (int m = 0; m < 4; ++m) { const size_t off = (size_t)(rin + ai * HALF + m * 16) * D + col;
;                     if (u.split) { float* sp = (float*)(P.ws + WS_SLAB) + ((size_t)u.sl * (NB * CTX) + (size_t)b * CTX) * D + off;
;                         *(f32x4*)sp = g0 * acc[ai][bj][m][0]; *(f32x4*)(sp + 4) = g1 * acc[ai][bj][m][1]; }
;                     else { const f32x4 x0 = *(const f32x4*)(rbase + off), x1 = *(const f32x4*)(rbase + off + 4);
;                         *(f32x4*)(dbase + off) = x0 + g0 * acc[ai][bj][m][0]; *(f32x4*)(dbase + off + 4) = x1 + g1 * acc[ai][bj][m][1]; } } }
	v_pk_fma_f32 v[222:223], v[222:223], v[214:215], v[246:247]
	v_pk_fma_f32 v[224:225], v[224:225], v[216:217], v[248:249]
	s_add_u32 s76, s76, 0x10000
	s_addc_u32 s77, s77, 0
	global_store_dwordx4 v210, v[222:225], s[76:77]
	global_load_dwordx4 v[246:249], v210, s[74:75] offset:512
	s_waitcnt vmcnt(10) lgkmcnt(4)
	v_pk_fma_f32 v[226:227], v[226:227], v[214:215], v[192:193]
	v_pk_fma_f32 v[228:229], v[228:229], v[216:217], v[194:195]
	global_store_dwordx4 v211, v[226:229], s[76:77]
	global_load_dwordx4 v[192:195], v211, s[74:75] offset:512
	ds_write_b128 v207, v[76:79]
	ds_write_b128 v208, v[72:75]
	ds_read_b128 v[222:225], v209
	ds_read_b128 v[226:229], v209 offset:8192
	s_waitcnt vmcnt(10) lgkmcnt(5)
	v_pk_fma_f32 v[230:231], v[230:231], v[218:219], v[196:197]
	v_pk_fma_f32 v[232:233], v[232:233], v[220:221], v[198:199]
	global_store_dwordx4 v210, v[230:233], s[76:77] offset:512
	s_add_u32 s74, s74, 0x10000
	s_addc_u32 s75, s75, 0
	global_load_dwordx4 v[196:199], v210, s[74:75]
	s_waitcnt vmcnt(10) lgkmcnt(4)
	v_pk_fma_f32 v[234:235], v[234:235], v[218:219], v[186:187]
	v_pk_fma_f32 v[236:237], v[236:237], v[220:221], v[188:189]
	global_store_dwordx4 v211, v[234:237], s[76:77] offset:512
	global_load_dwordx4 v[186:189], v211, s[74:75]
	ds_write_b128 v207, v[12:15]
	ds_write_b128 v208, v[8:11]
	ds_read_b128 v[230:233], v209
	ds_read_b128 v[234:237], v209 offset:8192
	s_waitcnt vmcnt(10) lgkmcnt(5)
	v_pk_fma_f32 v[222:223], v[222:223], v[214:215], v[238:239]
	v_pk_fma_f32 v[224:225], v[224:225], v[216:217], v[240:241]
	s_add_u32 s76, s76, 0x10000
	s_addc_u32 s77, s77, 0
	global_store_dwordx4 v210, v[222:225], s[76:77]
	global_load_dwordx4 v[238:241], v210, s[74:75] offset:512
	s_waitcnt vmcnt(10) lgkmcnt(4)
	v_pk_fma_f32 v[226:227], v[226:227], v[214:215], v[242:243]
	v_pk_fma_f32 v[228:229], v[228:229], v[216:217], v[244:245]
	global_store_dwordx4 v211, v[226:229], s[76:77]
	global_load_dwordx4 v[242:245], v211, s[74:75] offset:512
	ds_write_b128 v207, v[68:71]
	ds_write_b128 v208, v[64:67]
	ds_read_b128 v[222:225], v209
	ds_read_b128 v[226:229], v209 offset:8192
	s_waitcnt vmcnt(10) lgkmcnt(5)
	v_pk_fma_f32 v[230:231], v[230:231], v[218:219], v[246:247]
	v_pk_fma_f32 v[232:233], v[232:233], v[220:221], v[248:249]
	global_store_dwordx4 v210, v[230:233], s[76:77] offset:512
	s_waitcnt vmcnt(9) lgkmcnt(4)
	v_pk_fma_f32 v[234:235], v[234:235], v[218:219], v[192:193]
	v_pk_fma_f32 v[236:237], v[236:237], v[220:221], v[194:195]
	global_store_dwordx4 v211, v[234:237], s[76:77] offset:512
	ds_write_b128 v207, v[4:7]
	ds_write_b128 v208, v[0:3]
	ds_read_b128 v[230:233], v209
	ds_read_b128 v[234:237], v209 offset:8192
	s_waitcnt vmcnt(8) lgkmcnt(5)
	v_pk_fma_f32 v[222:223], v[222:223], v[214:215], v[196:197]
	v_pk_fma_f32 v[224:225], v[224:225], v[216:217], v[198:199]
	s_add_u32 s76, s76, 0x10000
	s_addc_u32 s77, s77, 0
	global_store_dwordx4 v210, v[222:225], s[76:77]
	s_waitcnt vmcnt(7) lgkmcnt(4)
	v_pk_fma_f32 v[226:227], v[226:227], v[214:215], v[186:187]
	v_pk_fma_f32 v[228:229], v[228:229], v[216:217], v[188:189]
	global_store_dwordx4 v211, v[226:229], s[76:77]
	s_waitcnt vmcnt(6) lgkmcnt(1)
	v_pk_fma_f32 v[230:231], v[230:231], v[218:219], v[238:239]
	v_pk_fma_f32 v[232:233], v[232:233], v[220:221], v[240:241]
	global_store_dwordx4 v210, v[230:233], s[76:77] offset:512
	s_waitcnt vmcnt(5) lgkmcnt(0)
	v_pk_fma_f32 v[234:235], v[234:235], v[218:219], v[242:243]
	v_pk_fma_f32 v[236:237], v[236:237], v[220:221], v[244:245]
	global_store_dwordx4 v211, v[234:237], s[76:77] offset:512
	s_andn2_b64 vcc, exec, s[8:9]
	s_mov_b64 s[0:1], -1
	s_cbranch_vccnz .LBB0_976
	s_branch .Lepi_m2_after
